# first-barrier census loads batched + GLA decay-projection weight loads (gla_load_w2) four in flight instead of four serial round trips
# baseline (speedup 1.0000x reference)
.LBB0_297:
	v_mov_b32_e32 v5, 0
	v_mov_b32_e32 v8, 0
	v_mov_b32_e32 v9, 0
	v_mov_b32_e32 v10, 0
	s_and_saveexec_b64 s[44:45], vcc
	s_cbranch_execz .Lw2_skip_a
	v_ashrrev_i32_e32 v6, 5, v4
	v_ashrrev_i32_e32 v7, 31, v6
	v_lshl_add_u64 v[6:7], v[6:7], 2, v[2:3]
	global_load_dword v5, v[6:7], off
	global_load_dword v8, v[6:7], off offset:64
	global_load_dword v9, v[6:7], off offset:128
	global_load_dword v10, v[6:7], off offset:192
	s_waitcnt vmcnt(0)
	v_cvt_pk_bf16_f32 v5, v5, s0
	v_cvt_pk_bf16_f32 v8, v8, s0
	v_cvt_pk_bf16_f32 v9, v9, s0
	v_cvt_pk_bf16_f32 v10, v10, s0
.Lw2_skip_a:
	s_or_b64 exec, exec, s[44:45]
	ds_write_b16 v0, v5
	ds_write_b16 v0, v8 offset:1024
	ds_write_b16 v0, v9 offset:2048
	ds_write_b16 v0, v10 offset:3072
	v_add_u32_e32 v0, 0x1000, v0

.LBB0_444:
	v_mov_b32_e32 v9, 0
	v_mov_b32_e32 v12, 0
	v_mov_b32_e32 v13, 0
	v_mov_b32_e32 v14, 0
	s_and_saveexec_b64 s[8:9], vcc
	s_cbranch_execz .Lw2_skip_c
	v_ashrrev_i32_e32 v10, 5, v8
	v_ashrrev_i32_e32 v11, 31, v10
	v_lshl_add_u64 v[10:11], v[10:11], 2, v[2:3]
	global_load_dword v9, v[10:11], off
	global_load_dword v12, v[10:11], off offset:64
	global_load_dword v13, v[10:11], off offset:128
	global_load_dword v14, v[10:11], off offset:192
	s_waitcnt vmcnt(0)
	v_cvt_pk_bf16_f32 v9, v9, s0
	v_cvt_pk_bf16_f32 v12, v12, s0
	v_cvt_pk_bf16_f32 v13, v13, s0
	v_cvt_pk_bf16_f32 v14, v14, s0
.Lw2_skip_c:
	s_or_b64 exec, exec, s[8:9]
	ds_write_b16 v0, v9
	ds_write_b16 v0, v12 offset:1024
	ds_write_b16 v0, v13 offset:2048
	ds_write_b16 v0, v14 offset:3072
	v_add_u32_e32 v0, 0x1000, v0
